# GDN scan: LDS-DMA ring runs one more stage ahead (refills the slot read in the previous step; counted wait vmcnt(52)); latency tolerance 3 -> 4 steps
# baseline (speedup 1.0000x reference)
; #define LAS __attribute__((address_space(3)))
; DI f32x16 zero16() { f32x16 z; for (int i = 0; i < 16; ++i) z[i] = 0.f; return z; }
; DI void phase_scan(KArgs args, LAS unsigned char* L, const Ctx& c) {
;     if (c.slab == NSLAB - 1 && c.bid >= 24 && c.bid < 40) { phase_select(args, L, c, c.bid - 24); return; }
;     const int nwu = c.nseq * 24, wu = c.bid;
;     if (wu < nwu && c.wave == 0) {
;         const int lane = c.lane;
;         const int chain = wu >> 1, nt = wu & 1, seq = chain / 12, rem = chain % 12, head = rem >> 1, dir = rem & 1;
;         const int nch = c.seqlen >> 6, gch0 = seq * nch;
;         unsigned char* GS = BIGP(unsigned char, B_GSCR);
;         f32x16 S[2]; S[0] = zero16(); S[1] = zero16();
;         bf16x8 A[2][2][4]; u32x4 cm[2][2][2];
;         const long gstep = (long)(dir ? -1 : 1) * 12 * GSTRIDE;
;         const unsigned char* G0 = GS + (size_t)(((gch0 + (dir ? nch - 1 : 0)) * 6 + head) * 2 + dir) * GSTRIDE;
;         unsigned char* Gs = (unsigned char*)G0;
;         float glv[4];
; #pragma unroll
;         for (int q = 0; q < 4; ++q) { const int sq = q * 64 + lane; glv[q] = *(const float*)(G0 + (long)(sq < nch ? sq : nch - 1) * gstep + 40960); }
;         LAS unsigned char* RING = L + 81920;
;         int dslot = 0, rslot = 0, dstage = 0;
;     ...
;         SCAN_DMA(); SCAN_DMA(); SCAN_DMA(); SCAN_DMA(); SCAN_DMA();
.LBB0_646:
	s_movk_i32 s33, 0x600
	s_and_b64 vcc, exec, s[0:1]
	s_cbranch_vccz .LBB0_946
	v_readlane_b32 s2, v254, 23
	s_lshr_b32 s30, s60, 6
	v_readlane_b32 s3, v254, 24
	s_and_b64 s[0:1], s[2:3], exec
	s_cselect_b32 s0, 6, 8
	s_add_i32 s31, s30, -1
	v_writelane_b32 v254, s0, 32
	s_and_b64 s[0:1], s[2:3], exec
	s_cselect_b32 s2, 0xc0, 24
	s_cmp_lt_u32 s61, 64
	s_cselect_b64 s[0:1], -1, 0
	s_cmp_lt_i32 s68, s2
	s_cselect_b64 s[2:3], -1, 0
	s_and_b64 s[0:1], s[2:3], s[0:1]
	s_andn2_b64 vcc, exec, s[0:1]
	s_movk_i32 s27, 0x90
	v_readlane_b32 s28, v254, 27
	v_readlane_b32 s29, v254, 29
	s_cbranch_vccnz .LBB0_651
	s_setprio 3
	s_ashr_i32 s0, s68, 1
	s_mul_hi_i32 s1, s0, 0x2aaaaaab
	s_lshr_b32 s2, s1, 31
	s_ashr_i32 s1, s1, 1
	s_add_i32 s1, s1, s2
	s_mul_i32 s2, s1, 12
	s_sub_i32 s2, s0, s2
	v_readlane_b32 s4, v254, 32
	s_bfe_i32 s3, s2, 0x10000
	s_and_b32 s0, s2, 1
	s_lshl_b32 s4, s1, s4
	s_cmp_eq_u32 s0, 0
	s_mov_b32 s0, 0x78c00
	s_cselect_b32 s1, 0, -1
	s_cselect_b32 s0, s0, 0xfff87400
	s_and_b32 s3, s3, s31
	s_add_i32 s3, s3, s4
	s_mul_i32 s3, s3, 12
	s_add_i32 s24, s3, s2
	s_mul_hi_i32 s23, s24, 0xa100
	s_mul_i32 s24, s24, 0xa100
	s_waitcnt lgkmcnt(0)
	s_add_u32 s6, s72, s24
	s_addc_u32 s7, s73, s23
	s_add_u32 s2, s6, 0x37800000
	s_addc_u32 s3, s7, 0
	v_min_i32_e32 v1, s31, v28
	v_mov_b64_e32 v[4:5], s[2:3]
	v_mad_u64_u32 v[6:7], s[4:5], s0, v1, v[4:5]
	v_mad_i32_i24 v1, s1, v1, v7
	v_or_b32_e32 v7, 64, v28
	v_min_i32_e32 v2, s31, v7
	v_mad_u64_u32 v[8:9], s[4:5], s0, v2, v[4:5]
	v_or_b32_e32 v12, 0x80, v28
	v_mad_i32_i24 v9, s1, v2, v9
	v_min_i32_e32 v2, s31, v12
	v_mad_u64_u32 v[10:11], s[4:5], s0, v2, v[4:5]
	v_or_b32_e32 v13, 0xc0, v28
	v_mad_i32_i24 v11, s1, v2, v11
	v_min_i32_e32 v2, s31, v13
	v_mad_u64_u32 v[4:5], s[4:5], s0, v2, v[4:5]
	s_add_u32 s20, s6, 0x37802000
	s_addc_u32 s21, s7, 0
	s_lshl_b32 s4, s68, 12
	s_and_b32 s25, s4, 0x1000
	s_add_u32 s18, s2, s0
	s_addc_u32 s19, s3, s1
	s_add_u32 s16, s18, 0x2000
	s_addc_u32 s17, s19, 0
	s_add_u32 s14, s18, s0
	s_addc_u32 s15, s19, s1
	s_add_u32 s12, s14, 0x2000
	s_addc_u32 s13, s15, 0
	s_add_u32 s10, s14, s0
	s_addc_u32 s11, s15, s1
	s_mov_b32 s26, 0xa000
	s_add_u32 s8, s10, 0x2000
	v_add_co_u32_e32 v6, vcc, s26, v6
	v_lshlrev_b32_e32 v148, 4, v7
	s_addc_u32 s9, s11, 0
	v_addc_co_u32_e32 v7, vcc, 0, v1, vcc
	s_add_u32 s6, s10, s0
	v_add_co_u32_e32 v8, vcc, s26, v8
	s_addc_u32 s7, s11, s1
	s_nop 0
	v_addc_co_u32_e32 v9, vcc, 0, v9, vcc
	s_add_u32 s4, s6, 0x2000
	v_add_co_u32_e32 v10, vcc, s26, v10
	s_addc_u32 s5, s7, 0
	s_add_i32 s22, 0, 0x14000
	v_addc_co_u32_e32 v11, vcc, 0, v11, vcc
	v_mad_i32_i24 v5, s1, v2, v5
	v_lshlrev_b32_e32 v2, 4, v28
	v_add_co_u32_e32 v4, vcc, s26, v4
	s_mov_b32 m0, s22
	v_readlane_b32 s26, v253, 5
	v_addc_co_u32_e32 v5, vcc, 0, v5, vcc
	global_load_dword v1, v[6:7], off
	global_load_dword v168, v[8:9], off
	global_load_dword v169, v[10:11], off
	global_load_dword v170, v[4:5], off
	v_lshlrev_b32_e32 v150, 4, v12
	global_load_lds_dwordx4 v2, s[2:3]
	s_mov_b32 m0, s26
	v_readlane_b32 s26, v253, 6
	global_load_lds_dwordx4 v148, s[2:3]
	s_mov_b32 m0, s26
	v_readlane_b32 s26, v253, 7
	v_lshlrev_b32_e32 v152, 4, v13
	global_load_lds_dwordx4 v150, s[2:3]
	s_mov_b32 m0, s26
	v_readlane_b32 s26, v253, 8
	v_or_b32_e32 v154, 0x1000, v2
	global_load_lds_dwordx4 v152, s[2:3]
	s_mov_b32 m0, s26
	v_readlane_b32 s26, v253, 9
	v_or_b32_e32 v156, 0x1400, v2
	global_load_lds_dwordx4 v154, s[2:3]
	s_mov_b32 m0, s26
	v_readlane_b32 s26, v253, 10
	v_or_b32_e32 v158, 0x1800, v2
	global_load_lds_dwordx4 v156, s[2:3]
	s_mov_b32 m0, s26
	v_readlane_b32 s26, v253, 11
	v_or_b32_e32 v160, 0x1c00, v2
	v_lshl_or_b32 v162, v28, 5, s25
	v_mov_b32_e32 v163, v3
	global_load_lds_dwordx4 v158, s[2:3]
	s_mov_b32 m0, s26
	v_lshl_add_u64 v[12:13], s[20:21], 0, v[162:163]
	global_load_lds_dwordx4 v160, s[2:3]
	s_add_i32 m0, 0, 0x16000
	v_readlane_b32 s26, v253, 12
	v_lshl_add_u64 v[12:13], v[12:13], 0, 16
	global_load_lds_dwordx4 v162, s[20:21]
	s_mov_b32 m0, s26
	v_readlane_b32 s26, v253, 13
	v_or_b32_e32 v164, 0x800, v162
	v_mov_b32_e32 v165, v3
	global_load_lds_dwordx4 v[12:13], off
	s_mov_b32 m0, s26
	v_lshl_add_u64 v[14:15], s[20:21], 0, v[164:165]
	global_load_lds_dwordx4 v164, s[20:21]
	v_readlane_b32 s20, v253, 14
	v_lshl_add_u64 v[14:15], v[14:15], 0, 16
	s_mov_b32 m0, s20
	v_readlane_b32 s21, v253, 15
	global_load_lds_dwordx4 v[14:15], off
	s_mov_b32 m0, s21
	v_readlane_b32 s20, v253, 16
	global_load_lds_dwordx4 v2, s[18:19]
	s_mov_b32 m0, s20
	v_readlane_b32 s20, v253, 17
	global_load_lds_dwordx4 v148, s[18:19]
	s_mov_b32 m0, s20
	v_readlane_b32 s20, v253, 18
	global_load_lds_dwordx4 v150, s[18:19]
	s_mov_b32 m0, s20
	v_readlane_b32 s20, v253, 19
	global_load_lds_dwordx4 v152, s[18:19]
	s_add_i32 m0, 0, 0x18000
	v_lshl_add_u64 v[16:17], s[16:17], 0, v[162:163]
	global_load_lds_dwordx4 v154, s[18:19]
	s_mov_b32 m0, s20
	v_readlane_b32 s20, v253, 4
	global_load_lds_dwordx4 v156, s[18:19]
	s_mov_b32 m0, s20
	v_readlane_b32 s20, v253, 20
	global_load_lds_dwordx4 v158, s[18:19]
	s_mov_b32 m0, s20
	v_lshl_add_u64 v[16:17], v[16:17], 0, 16
	global_load_lds_dwordx4 v160, s[18:19]
	s_add_i32 m0, 0, 0x19000
	v_readlane_b32 s18, v253, 21
	global_load_lds_dwordx4 v162, s[16:17]
	s_mov_b32 m0, s18
	v_readlane_b32 s18, v253, 22
	global_load_lds_dwordx4 v[16:17], off
	s_mov_b32 m0, s18
	v_lshl_add_u64 v[18:19], s[16:17], 0, v[164:165]
	global_load_lds_dwordx4 v164, s[16:17]
	v_readlane_b32 s16, v253, 23
	v_lshl_add_u64 v[18:19], v[18:19], 0, 16
	s_mov_b32 m0, s16
	v_readlane_b32 s16, v253, 24
	global_load_lds_dwordx4 v[18:19], off
	s_add_i32 m0, 0, 0x1a000
	v_lshl_add_u64 v[20:21], s[12:13], 0, v[162:163]
; DI void phase_scan(KArgs args, LAS unsigned char* L, const Ctx& c) {
;     ...
;         SCAN_DMA(); SCAN_DMA(); SCAN_DMA(); SCAN_DMA(); SCAN_DMA();
;         asm volatile("s_waitcnt vmcnt(48)" ::: "memory"); SCAN_LOAD(0);
;         asm volatile("s_waitcnt vmcnt(36)" ::: "memory"); SCAN_LOAD(1);
;         for (int step = 0; step < nch; step += 2) {
;             SCAN_STEP(0, step);     asm volatile("s_waitcnt vmcnt(24)" ::: "memory"); SCAN_LOAD(0); SCAN_DMA();
;             SCAN_STEP(1, step + 1); asm volatile("s_waitcnt vmcnt(24)" ::: "memory"); SCAN_LOAD(1); SCAN_DMA();
;         }
	global_load_lds_dwordx4 v2, s[14:15]
	s_mov_b32 m0, s16
	v_readlane_b32 s16, v253, 25
	global_load_lds_dwordx4 v148, s[14:15]
	s_mov_b32 m0, s16
	v_readlane_b32 s16, v253, 26
	global_load_lds_dwordx4 v150, s[14:15]
	s_mov_b32 m0, s16
	v_readlane_b32 s16, v253, 27
	global_load_lds_dwordx4 v152, s[14:15]
	s_mov_b32 m0, s16
	v_readlane_b32 s16, v253, 28
	global_load_lds_dwordx4 v154, s[14:15]
	s_mov_b32 m0, s16
	v_readlane_b32 s16, v253, 29
	global_load_lds_dwordx4 v156, s[14:15]
	s_mov_b32 m0, s16
	v_readlane_b32 s16, v253, 30
	global_load_lds_dwordx4 v158, s[14:15]
	s_mov_b32 m0, s16
	v_lshl_add_u64 v[20:21], v[20:21], 0, 16
	global_load_lds_dwordx4 v160, s[14:15]
	s_add_i32 m0, 0, 0x1c000
	v_readlane_b32 s14, v253, 31
	global_load_lds_dwordx4 v162, s[12:13]
	s_mov_b32 m0, s14
	v_readlane_b32 s14, v253, 32
	global_load_lds_dwordx4 v[20:21], off
	s_mov_b32 m0, s14
	v_lshl_add_u64 v[22:23], s[12:13], 0, v[164:165]
	global_load_lds_dwordx4 v164, s[12:13]
	v_readlane_b32 s12, v253, 33
	v_lshl_add_u64 v[22:23], v[22:23], 0, 16
	s_mov_b32 m0, s12
	v_readlane_b32 s12, v253, 34
	global_load_lds_dwordx4 v[22:23], off
	s_mov_b32 m0, s12
	v_readlane_b32 s12, v253, 35
	global_load_lds_dwordx4 v2, s[10:11]
	s_mov_b32 m0, s12
	v_readlane_b32 s12, v253, 36
	global_load_lds_dwordx4 v148, s[10:11]
	s_mov_b32 m0, s12
	v_readlane_b32 s12, v253, 37
	global_load_lds_dwordx4 v150, s[10:11]
	s_mov_b32 m0, s12
	v_readlane_b32 s12, v253, 38
	global_load_lds_dwordx4 v152, s[10:11]
	s_add_i32 m0, 0, 0x1e000
	v_lshl_add_u64 v[24:25], s[8:9], 0, v[162:163]
	global_load_lds_dwordx4 v154, s[10:11]
	s_mov_b32 m0, s12
	v_readlane_b32 s12, v253, 39
	global_load_lds_dwordx4 v156, s[10:11]
	s_mov_b32 m0, s12
	v_readlane_b32 s12, v253, 40
	global_load_lds_dwordx4 v158, s[10:11]
	s_mov_b32 m0, s12
	v_lshl_add_u64 v[24:25], v[24:25], 0, 16
	global_load_lds_dwordx4 v160, s[10:11]
	v_readlane_b32 s10, v253, 41
	s_mov_b32 m0, s10
	v_readlane_b32 s10, v253, 42
	global_load_lds_dwordx4 v162, s[8:9]
	s_mov_b32 m0, s10
	v_readlane_b32 s10, v253, 43
	global_load_lds_dwordx4 v[24:25], off
	s_mov_b32 m0, s10
	v_lshl_add_u64 v[26:27], s[8:9], 0, v[164:165]
	global_load_lds_dwordx4 v164, s[8:9]
	v_readlane_b32 s8, v253, 44
	v_lshl_add_u64 v[26:27], v[26:27], 0, 16
	s_mov_b32 m0, s8
	v_readlane_b32 s8, v253, 45
	global_load_lds_dwordx4 v[26:27], off
	s_add_i32 m0, 0, 0x20000
	v_lshl_add_u64 v[28:29], s[4:5], 0, v[162:163]
	global_load_lds_dwordx4 v2, s[6:7]
	s_mov_b32 m0, s8
	v_readlane_b32 s8, v253, 46
	global_load_lds_dwordx4 v148, s[6:7]
	s_mov_b32 m0, s8
	v_readlane_b32 s8, v253, 47
	global_load_lds_dwordx4 v150, s[6:7]
	s_mov_b32 m0, s8
	v_readlane_b32 s8, v253, 48
	global_load_lds_dwordx4 v152, s[6:7]
	s_mov_b32 m0, s8
	v_readlane_b32 s8, v253, 49
	global_load_lds_dwordx4 v154, s[6:7]
	s_mov_b32 m0, s8
	v_readlane_b32 s8, v253, 50
	global_load_lds_dwordx4 v156, s[6:7]
	s_mov_b32 m0, s8
	v_readlane_b32 s8, v253, 51
	global_load_lds_dwordx4 v158, s[6:7]
	s_mov_b32 m0, s8
	v_lshl_add_u64 v[28:29], v[28:29], 0, 16
	global_load_lds_dwordx4 v160, s[6:7]
	s_add_i32 m0, 0, 0x22000
	v_readlane_b32 s6, v253, 52
	global_load_lds_dwordx4 v162, s[4:5]
	s_mov_b32 m0, s6
	v_readlane_b32 s6, v253, 53
	global_load_lds_dwordx4 v[28:29], off
	s_mov_b32 m0, s6
	v_lshl_add_u64 v[30:31], s[4:5], 0, v[164:165]
	global_load_lds_dwordx4 v164, s[4:5]
	v_readlane_b32 s4, v253, 54
	v_lshl_add_u64 v[30:31], v[30:31], 0, 16
	s_mov_b32 m0, s4
	v_add_u32_e32 v171, s22, v2
	global_load_lds_dwordx4 v[30:31], off
	s_waitcnt vmcnt(48)
	ds_read_b128 v[76:79], v171
	ds_read_b128 v[80:83], v171 offset:1024
	ds_read_b128 v[84:87], v171 offset:2048
	ds_read_b128 v[88:91], v171 offset:3072
	ds_read_b128 v[96:99], v171 offset:8192
	ds_read_b128 v[92:95], v171 offset:9216
	ds_read_b128 v[36:39], v171 offset:4096
	ds_read_b128 v[40:43], v171 offset:5120
	ds_read_b128 v[44:47], v171 offset:6144
	ds_read_b128 v[48:51], v171 offset:7168
	ds_read_b128 v[72:75], v171 offset:10240
	ds_read_b128 v[52:55], v171 offset:11264
	s_waitcnt vmcnt(36)
	v_add_u32_e32 v4, s21, v2
	s_waitcnt vmcnt(0)
	ds_read_b128 v[100:103], v4 offset:11264
	ds_read_b128 v[104:107], v4 offset:10240
	ds_read_b128 v[56:59], v4 offset:7168
	ds_read_b128 v[60:63], v4 offset:6144
	ds_read_b128 v[64:67], v4 offset:5120
	ds_read_b128 v[68:71], v4 offset:4096
	ds_read_b128 v[124:127], v4 offset:9216
	ds_read_b128 v[128:131], v4 offset:8192
	ds_read_b128 v[108:111], v4 offset:3072
	ds_read_b128 v[112:115], v4 offset:2048
	ds_read_b128 v[116:119], v4 offset:1024
	ds_read_b128 v[120:123], v4
	s_add_u32 s4, s24, s25
	s_addc_u32 s5, s23, 0
	s_add_u32 s4, s72, s4
	s_addc_u32 s5, s73, s5
	v_lshl_add_u64 v[4:5], s[4:5], 0, v[2:3]
	s_mov_b64 s[4:5], 0x37808800
	v_lshl_add_u64 v[166:167], v[4:5], 0, s[4:5]
	v_mov_b32_e32 v4, 0
	s_mov_b32 s11, 1
	v_mov_b32_e32 v149, v3
	v_mov_b32_e32 v151, v3
	v_mov_b32_e32 v153, v3
	v_mov_b32_e32 v155, v3
	v_mov_b32_e32 v157, v3
	v_mov_b32_e32 v159, v3
	v_mov_b32_e32 v161, v3
	s_lshl_b64 s[8:9], s[0:1], 1
	s_mov_b32 s12, 2
	s_mov_b32 s10, 6
	v_mov_b32_e32 v5, v4
	v_mov_b32_e32 v6, v4
	v_mov_b32_e32 v7, v4
	v_mov_b32_e32 v8, v4
	v_mov_b32_e32 v9, v4
	v_mov_b32_e32 v10, v4
	v_mov_b32_e32 v11, v4
	v_mov_b32_e32 v12, v4
	v_mov_b32_e32 v13, v4
	v_mov_b32_e32 v14, v4
	v_mov_b32_e32 v15, v4
	v_mov_b32_e32 v16, v4
	v_mov_b32_e32 v17, v4
	v_mov_b32_e32 v18, v4
	v_mov_b32_e32 v19, v4
	v_mov_b32_e32 v20, v4
	v_mov_b32_e32 v21, v4
	v_mov_b32_e32 v22, v4
	v_mov_b32_e32 v23, v4
	v_mov_b32_e32 v24, v4
	v_mov_b32_e32 v25, v4
	v_mov_b32_e32 v26, v4
	v_mov_b32_e32 v27, v4
	v_mov_b32_e32 v28, v4
	v_mov_b32_e32 v29, v4
	v_mov_b32_e32 v30, v4
	v_mov_b32_e32 v31, v4
	v_mov_b32_e32 v32, v4
	v_mov_b32_e32 v33, v4
	v_mov_b32_e32 v34, v4
	v_mov_b32_e32 v35, v4
	s_waitcnt lgkmcnt(0)
	s_mul_i32 s5, s1, 5
	s_mul_hi_u32 s6, s0, 5
	s_add_i32 s5, s5, s6
	s_mul_i32 s4, s0, 5
	s_add_u32 s4, s2, s4
	s_addc_u32 s5, s3, s5
	s_mov_b32 m0, s22
	s_nop 0
	global_load_lds_dwordx4 v2, s[4:5]
	s_add_i32 m0, s22, 0x400
	s_nop 0
	global_load_lds_dwordx4 v148, s[4:5]
	s_add_i32 m0, s22, 0x800
	s_nop 0
	global_load_lds_dwordx4 v150, s[4:5]
	s_add_i32 m0, s22, 0xc00
	s_nop 0
	global_load_lds_dwordx4 v152, s[4:5]
	s_add_i32 m0, s22, 0x1000
	s_nop 0
	global_load_lds_dwordx4 v154, s[4:5]
	s_add_i32 m0, s22, 0x1400
	s_nop 0
	global_load_lds_dwordx4 v156, s[4:5]
	s_add_i32 m0, s22, 0x1800
	s_nop 0
	global_load_lds_dwordx4 v158, s[4:5]
	s_add_i32 m0, s22, 0x1c00
	s_nop 0
	global_load_lds_dwordx4 v160, s[4:5]
	s_add_u32 s4, s4, 0x2000
	s_addc_u32 s5, s5, 0
	v_lshl_add_u64 v[132:133], s[4:5], 0, v[162:163]
	s_add_i32 m0, s22, 0x2000
	s_nop 0
	global_load_lds_dwordx4 v[132:133], off
	v_lshl_add_u64 v[132:133], v[132:133], 0, 16
	s_add_i32 m0, s22, 0x2400
	s_nop 0
	global_load_lds_dwordx4 v[132:133], off
	v_lshl_add_u64 v[132:133], s[4:5], 0, v[164:165]
	s_add_i32 m0, s22, 0x2800
	s_nop 0
	global_load_lds_dwordx4 v[132:133], off
	v_lshl_add_u64 v[132:133], v[132:133], 0, 16
	s_add_i32 m0, s22, 0x2c00
	s_nop 0
	global_load_lds_dwordx4 v[132:133], off
; DI void phase_scan(KArgs args, LAS unsigned char* L, const Ctx& c) {
;     ...
;         SCAN_DMA(); SCAN_DMA(); SCAN_DMA(); SCAN_DMA(); SCAN_DMA();
;         asm volatile("s_waitcnt vmcnt(48)" ::: "memory"); SCAN_LOAD(0);
;         asm volatile("s_waitcnt vmcnt(36)" ::: "memory"); SCAN_LOAD(1);
;         for (int step = 0; step < nch; step += 2) {
;             SCAN_STEP(0, step);     asm volatile("s_waitcnt vmcnt(24)" ::: "memory"); SCAN_LOAD(0); SCAN_DMA();
;             SCAN_STEP(1, step + 1); asm volatile("s_waitcnt vmcnt(24)" ::: "memory"); SCAN_LOAD(1); SCAN_DMA();
.LBB0_649:
	s_add_i32 s14, s10, -6
	s_mov_b32 s13, s10
	s_lshr_b32 s6, s14, 6
	s_cmp_lt_u32 s14, 64
	s_cselect_b64 vcc, -1, 0
	s_cmp_eq_u32 s6, 1
	s_cselect_b64 s[4:5], -1, 0
	s_cmp_eq_u32 s6, 2
	s_cselect_b64 s[6:7], -1, 0
	v_cndmask_b32_e64 v172, v170, v169, s[6:7]
	v_cndmask_b32_e64 v172, v172, v168, s[4:5]
	v_cndmask_b32_e32 v172, v172, v1, vcc
	s_waitcnt lgkmcnt(0)
	v_lshlrev_b32_e32 v174, 16, v96
	v_readlane_b32 s4, v172, s14
	v_and_b32_e32 v175, 0xffff0000, v96
	v_lshlrev_b32_e32 v96, 16, v97
	v_and_b32_e32 v97, 0xffff0000, v97
	v_cvt_pk_bf16_f32 v133, v6, v7
	v_pk_fma_f32 v[6:7], v[6:7], s[4:5], v[96:97] op_sel_hi:[1,0,1]
	v_lshlrev_b32_e32 v96, 16, v98
	v_and_b32_e32 v97, 0xffff0000, v98
	v_cvt_pk_bf16_f32 v134, v8, v9
	v_pk_fma_f32 v[8:9], v[8:9], s[4:5], v[96:97] op_sel_hi:[1,0,1]
	v_lshlrev_b32_e32 v96, 16, v99
	v_and_b32_e32 v97, 0xffff0000, v99
	v_cvt_pk_bf16_f32 v135, v10, v11
	v_pk_fma_f32 v[10:11], v[10:11], s[4:5], v[96:97] op_sel_hi:[1,0,1]
	v_lshlrev_b32_e32 v96, 16, v92
	v_and_b32_e32 v97, 0xffff0000, v92
	v_lshlrev_b32_e32 v92, 16, v93
	v_and_b32_e32 v93, 0xffff0000, v93
	v_cvt_pk_bf16_f32 v137, v14, v15
	v_pk_fma_f32 v[14:15], v[14:15], s[4:5], v[92:93] op_sel_hi:[1,0,1]
	v_lshlrev_b32_e32 v92, 16, v94
	v_and_b32_e32 v93, 0xffff0000, v94
	v_cvt_pk_bf16_f32 v138, v16, v17
	v_pk_fma_f32 v[16:17], v[16:17], s[4:5], v[92:93] op_sel_hi:[1,0,1]
	v_lshlrev_b32_e32 v92, 16, v95
	v_and_b32_e32 v93, 0xffff0000, v95
	v_cvt_pk_bf16_f32 v132, v4, v5
	v_cvt_pk_bf16_f32 v136, v12, v13
	v_cvt_pk_bf16_f32 v139, v18, v19
	v_pk_fma_f32 v[4:5], v[4:5], s[4:5], v[174:175] op_sel_hi:[1,0,1]
	v_pk_fma_f32 v[12:13], v[12:13], s[4:5], v[96:97] op_sel_hi:[1,0,1]
	v_pk_fma_f32 v[18:19], v[18:19], s[4:5], v[92:93] op_sel_hi:[1,0,1]
	v_cvt_pk_bf16_f32 v141, v22, v23
	v_cvt_pk_bf16_f32 v142, v24, v25
	v_mfma_f32_32x32x16_bf16 v[4:19], v[76:79], v[132:135], v[4:19]
	v_lshlrev_b32_e32 v76, 16, v72
	v_and_b32_e32 v77, 0xffff0000, v72
	v_lshlrev_b32_e32 v72, 16, v73
	v_and_b32_e32 v73, 0xffff0000, v73
	v_fma_f32 v22, v22, s4, v72
	v_fma_f32 v23, v23, s4, v73
	v_lshlrev_b32_e32 v72, 16, v74
	v_and_b32_e32 v73, 0xffff0000, v74
	v_pk_fma_f32 v[24:25], v[24:25], s[4:5], v[72:73] op_sel_hi:[1,0,1]
	v_lshlrev_b32_e32 v72, 16, v75
	v_and_b32_e32 v73, 0xffff0000, v75
	v_cvt_pk_bf16_f32 v143, v26, v27
	v_pk_fma_f32 v[26:27], v[26:27], s[4:5], v[72:73] op_sel_hi:[1,0,1]
	v_lshlrev_b32_e32 v72, 16, v52
	v_and_b32_e32 v73, 0xffff0000, v52
	v_lshlrev_b32_e32 v52, 16, v53
	v_and_b32_e32 v53, 0xffff0000, v53
	v_cvt_pk_bf16_f32 v145, v30, v31
	v_pk_fma_f32 v[30:31], v[30:31], s[4:5], v[52:53] op_sel_hi:[1,0,1]
	v_lshlrev_b32_e32 v52, 16, v54
	v_and_b32_e32 v53, 0xffff0000, v54
	v_cvt_pk_bf16_f32 v146, v32, v33
	v_pk_fma_f32 v[32:33], v[32:33], s[4:5], v[52:53] op_sel_hi:[1,0,1]
	v_lshlrev_b32_e32 v52, 16, v55
	v_and_b32_e32 v53, 0xffff0000, v55
	v_cvt_pk_bf16_f32 v140, v20, v21
	v_cvt_pk_bf16_f32 v144, v28, v29
	v_cvt_pk_bf16_f32 v147, v34, v35
	v_pk_fma_f32 v[20:21], v[20:21], s[4:5], v[76:77] op_sel_hi:[1,0,1]
	v_pk_fma_f32 v[28:29], v[28:29], s[4:5], v[72:73] op_sel_hi:[1,0,1]
	v_pk_fma_f32 v[34:35], v[34:35], s[4:5], v[52:53] op_sel_hi:[1,0,1]
	v_mfma_f32_32x32x16_bf16 v[4:19], v[80:83], v[136:139], v[4:19]
	s_mul_i32 s4, s12, 0x3000
	v_add_u32_e32 v52, s4, v171
	s_min_i32 s4, s13, s31
	s_ashr_i32 s5, s4, 31
	s_mul_i32 s5, s0, s5
	s_mul_hi_u32 s7, s0, s4
	s_add_i32 s5, s7, s5
	v_mfma_f32_32x32x16_bf16 v[20:35], v[36:39], v[132:135], v[20:35]
	s_mul_i32 s7, s1, s4
	s_add_i32 s6, s12, 1
	s_add_i32 s5, s5, s7
	s_mul_i32 s4, s0, s4
	s_add_u32 s4, s2, s4
	s_mul_i32 s7, s11, 0x3000
	global_store_dwordx4 v[166:167], v[132:135], off offset:-2048
	global_store_dwordx4 v[166:167], v[136:139], off offset:-1024
	global_store_dwordx4 v[166:167], v[140:143], off
	global_store_dwordx4 v[166:167], v[144:147], off offset:1024
	v_mfma_f32_32x32x16_bf16 v[20:35], v[40:43], v[136:139], v[20:35]
	s_addc_u32 s5, s3, s5
	s_add_i32 s7, s22, s7
	s_waitcnt vmcnt(52)
	v_lshl_add_u64 v[132:133], s[4:5], 0, v[2:3]
	s_mov_b32 m0, s7
	v_and_b32_e32 v173, 0xffff0000, v128
	v_lshl_add_u64 v[174:175], v[166:167], 0, s[0:1]
	v_mfma_f32_32x32x16_bf16 v[4:19], v[84:87], v[140:143], v[4:19]
	v_lshl_add_u64 v[166:167], v[166:167], 0, s[8:9]
	v_mfma_f32_32x32x16_bf16 v[20:35], v[44:47], v[140:143], v[20:35]
	v_mfma_f32_32x32x16_bf16 v[4:19], v[88:91], v[144:147], v[4:19]
	v_mfma_f32_32x32x16_bf16 v[20:35], v[48:51], v[144:147], v[20:35]
	ds_read_b128 v[76:79], v52
	ds_read_b128 v[80:83], v52 offset:1024
	ds_read_b128 v[84:87], v52 offset:2048
	ds_read_b128 v[88:91], v52 offset:3072
	ds_read_b128 v[96:99], v52 offset:8192
	ds_read_b128 v[92:95], v52 offset:9216
	ds_read_b128 v[36:39], v52 offset:4096
	ds_read_b128 v[40:43], v52 offset:5120
	ds_read_b128 v[44:47], v52 offset:6144
	ds_read_b128 v[48:51], v52 offset:7168
	ds_read_b128 v[72:75], v52 offset:10240
	ds_read_b128 v[52:55], v52 offset:11264
	s_waitcnt lgkmcnt(12)
	global_load_lds_dwordx4 v[132:133], off
	v_lshl_add_u64 v[132:133], s[4:5], 0, v[148:149]
	s_add_i32 m0, s7, 0x400
	v_cvt_pk_bf16_f32 v134, v8, v9
	global_load_lds_dwordx4 v[132:133], off
	v_lshl_add_u64 v[132:133], s[4:5], 0, v[150:151]
	s_add_i32 m0, s7, 0x800
	v_cvt_pk_bf16_f32 v135, v10, v11
	global_load_lds_dwordx4 v[132:133], off
	v_lshl_add_u64 v[132:133], s[4:5], 0, v[152:153]
	s_add_i32 m0, s7, 0xc00
	v_cvt_pk_bf16_f32 v137, v14, v15
	global_load_lds_dwordx4 v[132:133], off
	v_lshl_add_u64 v[132:133], s[4:5], 0, v[154:155]
	s_add_i32 m0, s7, 0x1000
	v_cvt_pk_bf16_f32 v138, v16, v17
	global_load_lds_dwordx4 v[132:133], off
	v_lshl_add_u64 v[132:133], s[4:5], 0, v[156:157]
	s_add_i32 m0, s7, 0x1400
	v_cvt_pk_bf16_f32 v136, v12, v13
	global_load_lds_dwordx4 v[132:133], off
	v_lshl_add_u64 v[132:133], s[4:5], 0, v[158:159]
	s_add_i32 m0, s7, 0x1800
	v_cvt_pk_bf16_f32 v139, v18, v19
	global_load_lds_dwordx4 v[132:133], off
	s_add_i32 m0, s7, 0x1c00
	v_lshl_add_u64 v[132:133], s[4:5], 0, v[160:161]
	s_add_u32 s4, s4, 0x2000
	s_addc_u32 s5, s5, 0
	global_load_lds_dwordx4 v[132:133], off
	s_add_i32 m0, s7, 0x2000
	v_lshl_add_u64 v[132:133], s[4:5], 0, v[162:163]
	global_load_lds_dwordx4 v[132:133], off
	v_lshl_add_u64 v[132:133], v[132:133], 0, 16
	s_add_i32 m0, s7, 0x2400
	v_cvt_pk_bf16_f32 v140, v20, v21
	global_load_lds_dwordx4 v[132:133], off
	v_lshl_add_u64 v[132:133], s[4:5], 0, v[164:165]
	s_add_i32 m0, s7, 0x2800
	v_cvt_pk_bf16_f32 v141, v22, v23
	global_load_lds_dwordx4 v[132:133], off
	s_add_i32 m0, s7, 0x2c00
	s_cmp_lg_u32 s12, 4
	s_cselect_b32 s6, s6, 0
	s_add_i32 s4, s11, 1
	s_cmp_lg_u32 s11, 4
	s_cselect_b32 s7, s4, 0
	s_add_i32 s4, s10, -5
	v_lshl_add_u64 v[132:133], v[132:133], 0, 16
	v_readlane_b32 s4, v172, s4
	v_lshlrev_b32_e32 v172, 16, v128
	v_lshlrev_b32_e32 v128, 16, v129
	v_and_b32_e32 v129, 0xffff0000, v129
	global_load_lds_dwordx4 v[132:133], off
	v_cvt_pk_bf16_f32 v133, v6, v7
	v_pk_fma_f32 v[6:7], v[6:7], s[4:5], v[128:129] op_sel_hi:[1,0,1]
	v_lshlrev_b32_e32 v128, 16, v130
	v_and_b32_e32 v129, 0xffff0000, v130
	v_pk_fma_f32 v[8:9], v[8:9], s[4:5], v[128:129] op_sel_hi:[1,0,1]
	v_lshlrev_b32_e32 v128, 16, v131
	v_and_b32_e32 v129, 0xffff0000, v131
	v_pk_fma_f32 v[10:11], v[10:11], s[4:5], v[128:129] op_sel_hi:[1,0,1]
	v_lshlrev_b32_e32 v128, 16, v124
	v_and_b32_e32 v129, 0xffff0000, v124
	v_lshlrev_b32_e32 v124, 16, v125
	v_and_b32_e32 v125, 0xffff0000, v125
	v_pk_fma_f32 v[14:15], v[14:15], s[4:5], v[124:125] op_sel_hi:[1,0,1]
	v_lshlrev_b32_e32 v124, 16, v126
	v_and_b32_e32 v125, 0xffff0000, v126
	v_pk_fma_f32 v[16:17], v[16:17], s[4:5], v[124:125] op_sel_hi:[1,0,1]
	v_lshlrev_b32_e32 v124, 16, v127
	v_and_b32_e32 v125, 0xffff0000, v127
	v_cvt_pk_bf16_f32 v132, v4, v5
	v_pk_fma_f32 v[4:5], v[4:5], s[4:5], v[172:173] op_sel_hi:[1,0,1]
	v_pk_fma_f32 v[12:13], v[12:13], s[4:5], v[128:129] op_sel_hi:[1,0,1]
	v_pk_fma_f32 v[18:19], v[18:19], s[4:5], v[124:125] op_sel_hi:[1,0,1]
	v_cvt_pk_bf16_f32 v142, v24, v25
	v_cvt_pk_bf16_f32 v143, v26, v27
	v_mfma_f32_32x32x16_bf16 v[4:19], v[120:123], v[132:135], v[4:19]
	v_cvt_pk_bf16_f32 v144, v28, v29
	v_cvt_pk_bf16_f32 v145, v30, v31
	v_cvt_pk_bf16_f32 v146, v32, v33
	v_cvt_pk_bf16_f32 v147, v34, v35
	s_add_i32 s11, s6, 1
	global_store_dwordx4 v[174:175], v[132:135], off offset:-2048
	global_store_dwordx4 v[174:175], v[136:139], off offset:-1024
	global_store_dwordx4 v[174:175], v[140:143], off
	global_store_dwordx4 v[174:175], v[144:147], off offset:1024
	s_waitcnt vmcnt(52)
; DI void phase_scan(KArgs args, LAS unsigned char* L, const Ctx& c) {
;     ...
;         SCAN_DMA(); SCAN_DMA(); SCAN_DMA(); SCAN_DMA(); SCAN_DMA();
;         asm volatile("s_waitcnt vmcnt(48)" ::: "memory"); SCAN_LOAD(0);
;         asm volatile("s_waitcnt vmcnt(36)" ::: "memory"); SCAN_LOAD(1);
;         for (int step = 0; step < nch; step += 2) {
;             SCAN_STEP(0, step);     asm volatile("s_waitcnt vmcnt(24)" ::: "memory"); SCAN_LOAD(0); SCAN_DMA();
;             SCAN_STEP(1, step + 1); asm volatile("s_waitcnt vmcnt(24)" ::: "memory"); SCAN_LOAD(1); SCAN_DMA();
;         }
;         asm volatile("s_waitcnt vmcnt(0)" ::: "memory");
	v_mfma_f32_32x32x16_bf16 v[4:19], v[116:119], v[136:139], v[4:19]
	v_mfma_f32_32x32x16_bf16 v[4:19], v[112:115], v[140:143], v[4:19]
	v_mfma_f32_32x32x16_bf16 v[4:19], v[108:111], v[144:147], v[4:19]
	v_lshlrev_b32_e32 v108, 16, v104
	v_and_b32_e32 v109, 0xffff0000, v104
	v_lshlrev_b32_e32 v104, 16, v105
	v_and_b32_e32 v105, 0xffff0000, v105
	v_fma_f32 v22, v22, s4, v104
	v_fma_f32 v23, v23, s4, v105
	v_lshlrev_b32_e32 v104, 16, v106
	v_and_b32_e32 v105, 0xffff0000, v106
	v_pk_fma_f32 v[24:25], v[24:25], s[4:5], v[104:105] op_sel_hi:[1,0,1]
	v_lshlrev_b32_e32 v104, 16, v107
	v_and_b32_e32 v105, 0xffff0000, v107
	v_pk_fma_f32 v[26:27], v[26:27], s[4:5], v[104:105] op_sel_hi:[1,0,1]
	v_lshlrev_b32_e32 v104, 16, v100
	v_and_b32_e32 v105, 0xffff0000, v100
	v_lshlrev_b32_e32 v100, 16, v101
	v_and_b32_e32 v101, 0xffff0000, v101
	v_pk_fma_f32 v[30:31], v[30:31], s[4:5], v[100:101] op_sel_hi:[1,0,1]
	v_lshlrev_b32_e32 v100, 16, v102
	v_and_b32_e32 v101, 0xffff0000, v102
	v_pk_fma_f32 v[32:33], v[32:33], s[4:5], v[100:101] op_sel_hi:[1,0,1]
	v_lshlrev_b32_e32 v100, 16, v103
	v_and_b32_e32 v101, 0xffff0000, v103
	v_pk_fma_f32 v[20:21], v[20:21], s[4:5], v[108:109] op_sel_hi:[1,0,1]
	v_pk_fma_f32 v[28:29], v[28:29], s[4:5], v[104:105] op_sel_hi:[1,0,1]
	v_pk_fma_f32 v[34:35], v[34:35], s[4:5], v[100:101] op_sel_hi:[1,0,1]
	s_mul_i32 s4, s6, 0x3000
	v_add_u32_e32 v100, s4, v171
	v_mfma_f32_32x32x16_bf16 v[20:35], v[68:71], v[132:135], v[20:35]
	s_add_i32 s4, s10, 1
	s_min_i32 s4, s4, s31
	s_ashr_i32 s5, s4, 31
	s_mul_i32 s5, s0, s5
	s_mul_hi_u32 s12, s0, s4
	s_add_i32 s5, s12, s5
	s_mul_i32 s12, s1, s4
	s_add_i32 s5, s5, s12
	v_mfma_f32_32x32x16_bf16 v[20:35], v[64:67], v[136:139], v[20:35]
	s_mul_i32 s4, s0, s4
	s_add_u32 s4, s2, s4
	s_mul_i32 s12, s7, 0x3000
	s_addc_u32 s5, s3, s5
	s_add_i32 s12, s22, s12
	v_lshl_add_u64 v[132:133], s[4:5], 0, v[2:3]
	s_mov_b32 m0, s12
	v_mfma_f32_32x32x16_bf16 v[20:35], v[60:63], v[140:143], v[20:35]
	v_mfma_f32_32x32x16_bf16 v[20:35], v[56:59], v[144:147], v[20:35]
	ds_read_b128 v[120:123], v100
	ds_read_b128 v[116:119], v100 offset:1024
	ds_read_b128 v[112:115], v100 offset:2048
	ds_read_b128 v[108:111], v100 offset:3072
	ds_read_b128 v[128:131], v100 offset:8192
	ds_read_b128 v[124:127], v100 offset:9216
	ds_read_b128 v[68:71], v100 offset:4096
	ds_read_b128 v[64:67], v100 offset:5120
	ds_read_b128 v[60:63], v100 offset:6144
	ds_read_b128 v[56:59], v100 offset:7168
	ds_read_b128 v[104:107], v100 offset:10240
	ds_read_b128 v[100:103], v100 offset:11264
	s_waitcnt lgkmcnt(12)
	global_load_lds_dwordx4 v[132:133], off
	v_lshl_add_u64 v[132:133], s[4:5], 0, v[148:149]
	s_add_i32 m0, s12, 0x400
	s_nop 0
	global_load_lds_dwordx4 v[132:133], off
	v_lshl_add_u64 v[132:133], s[4:5], 0, v[150:151]
	s_add_i32 m0, s12, 0x800
	s_nop 0
	global_load_lds_dwordx4 v[132:133], off
	v_lshl_add_u64 v[132:133], s[4:5], 0, v[152:153]
	s_add_i32 m0, s12, 0xc00
	s_nop 0
	global_load_lds_dwordx4 v[132:133], off
	v_lshl_add_u64 v[132:133], s[4:5], 0, v[154:155]
	s_add_i32 m0, s12, 0x1000
	s_nop 0
	global_load_lds_dwordx4 v[132:133], off
	v_lshl_add_u64 v[132:133], s[4:5], 0, v[156:157]
	s_add_i32 m0, s12, 0x1400
	s_nop 0
	global_load_lds_dwordx4 v[132:133], off
	v_lshl_add_u64 v[132:133], s[4:5], 0, v[158:159]
	s_add_i32 m0, s12, 0x1800
	s_nop 0
	global_load_lds_dwordx4 v[132:133], off
	s_add_i32 m0, s12, 0x1c00
	v_lshl_add_u64 v[132:133], s[4:5], 0, v[160:161]
	s_add_u32 s4, s4, 0x2000
	s_addc_u32 s5, s5, 0
	global_load_lds_dwordx4 v[132:133], off
	s_add_i32 m0, s12, 0x2000
	v_lshl_add_u64 v[132:133], s[4:5], 0, v[162:163]
	global_load_lds_dwordx4 v[132:133], off
	v_lshl_add_u64 v[132:133], v[132:133], 0, 16
	s_add_i32 m0, s12, 0x2400
	s_nop 0
	global_load_lds_dwordx4 v[132:133], off
	v_lshl_add_u64 v[132:133], s[4:5], 0, v[164:165]
	s_add_i32 m0, s12, 0x2800
	s_nop 0
	global_load_lds_dwordx4 v[132:133], off
	v_lshl_add_u64 v[132:133], v[132:133], 0, 16
	s_add_i32 m0, s12, 0x2c00
	s_cmp_lg_u32 s6, 4
	global_load_lds_dwordx4 v[132:133], off
	s_cselect_b32 s12, s11, 0
	s_add_i32 s4, s7, 1
	s_cmp_lg_u32 s7, 4
	s_cselect_b32 s11, s4, 0
	s_add_i32 s4, s10, 2
	s_add_i32 s5, s10, -4
	s_cmp_ge_u32 s5, s30
	s_mov_b32 s10, s4
	s_cbranch_scc0 .LBB0_649
	s_waitcnt vmcnt(0)
	s_setprio 0
